# P1/P8 SwiGLU epilogue: h stores staged through per-wave LDS so 4 adjacent lanes write one 64-B run (coalesced lanes), testing store-issue model
# baseline (speedup 1.0000x reference)
; __device__ __forceinline__ unsigned cvt_pk_bf16(float lo, float hi) { unsigned r; asm volatile("v_cvt_pk_bf16_f32 %0, %1, %2" : "=v"(r) : "v"(lo), "v"(hi)); return r; }
; __device__ __forceinline__ float sigmoidf_(float x) { return __builtin_amdgcn_rcpf(1.f + __builtin_amdgcn_exp2f(-x * LOG2E)); }
;     __device__ __forceinline__ void operator()(const f32x4 (&acc)[2][2][4][2], const pg8::Unit& u, int wr, int wc, int fr, int fq) const {
;         const int row0 = u.pm * 256 + wr * 64 + fr, col0 = u.pn * 128 + wc * 32 + 8 * fq;
; #pragma unroll
;         for (int ai = 0; ai < 2; ++ai)
; #pragma unroll
;             for (int m = 0; m < 4; ++m) { const int row = row0 + ai * 128 + m * 16; const float rs = __builtin_amdgcn_rsqf(ss[row] * (1.f / DM) + EPS);
;                 float h[8];
; #pragma unroll
;                 for (int n = 0; n < 2; ++n)
; #pragma unroll
;                     for (int j = 0; j < 4; ++j) { const float g = acc[ai][0][m][n][j] * rs, up = acc[ai][1][m][n][j] * rs; h[4 * n + j] = g * sigmoidf_(g) * up; }
;                 u32x4 w; w.x = cvt_pk_bf16(h[0], h[1]); w.y = cvt_pk_bf16(h[2], h[3]); w.z = cvt_pk_bf16(h[4], h[5]); w.w = cvt_pk_bf16(h[6], h[7]);
;                 *(u32x4*)(H + (size_t)row * DFF + col0) = w; }
.LBB0_258:
	v_mbcnt_lo_u32_b32 v160, -1, 0
	v_mbcnt_hi_u32_b32 v160, -1, v160
	s_lshl_b32 s101, s96, 10
	s_add_u32 s101, s101, 0x20100
	v_lshlrev_b32_e32 v161, 4, v160
	v_add_u32_e32 v161, s101, v161
	v_and_b32_e32 v162, 15, v160
	v_lshrrev_b32_e32 v163, 4, v160
	v_lshlrev_b32_e32 v164, 6, v162
	v_lshl_add_u32 v164, v163, 4, v164
	v_add_u32_e32 v164, s101, v164
	v_lshrrev_b32_e32 v165, 2, v160
	v_sub_u32_e32 v165, v165, v162
	v_mul_i32_i24_e32 v165, 0x1600, v165
	v_and_b32_e32 v167, 3, v160
	v_sub_u32_e32 v167, v167, v163
	v_lshl_add_u32 v166, v167, 4, v165
	v_ashrrev_i32_e32 v167, 31, v166
	v_lshl_add_u32 v134, s44, 8, v233
	v_ashrrev_i32_e32 v135, 31, v134
	v_lshl_add_u64 v[136:137], v[134:135], 2, s[10:11]
	global_load_dword v0, v[136:137], off
	v_lshl_or_b32 v138, s42, 7, v235
	v_mov_b32_e32 v143, v124
	v_mov_b32_e32 v124, v121
	v_mov_b32_e32 v140, v130
	v_mov_b32_e32 v141, v126
	v_mov_b32_e32 v126, v131
	v_mov_b32_e32 v130, v132
	v_mov_b32_e32 v131, v128
	v_mov_b32_e32 v128, v133
	v_mov_b32_e32 v132, v118
	v_mov_b32_e32 v133, v122
	v_mov_b32_e32 v122, v119
	v_mov_b32_e32 v142, v120
	v_mov_b64_e32 v[118:119], s[18:19]
	v_ashrrev_i32_e32 v139, 31, v138
	v_mad_i64_i32 v[144:145], s[0:1], v134, s74, v[118:119]
	v_lshlrev_b64 v[120:121], 1, v[138:139]
	v_lshl_add_u64 v[138:139], v[144:145], 0, v[120:121]
	s_andn2_b64 vcc, exec, s[4:5]
	s_waitcnt vmcnt(0)
	v_fmamk_f32 v0, v0, 0x3a800000, v237
	v_rsq_f32_e32 v0, v0
	s_nop 0
	v_pk_mul_f32 v[124:125], v[124:125], v[0:1] op_sel_hi:[1,0]
	v_pk_mul_f32 v[140:141], v[140:141], v[0:1] op_sel_hi:[1,0]
	v_pk_mul_f32 v[126:127], v[126:127], v[0:1] op_sel_hi:[1,0]
	v_pk_mul_f32 v[130:131], v[130:131], v[0:1] op_sel_hi:[1,0]
	v_pk_mul_f32 v[128:129], v[128:129], v[0:1] op_sel_hi:[1,0]
	v_pk_mul_f32 v[132:133], v[132:133], v[0:1] op_sel_hi:[1,0]
	v_pk_mul_f32 v[122:123], v[122:123], v[0:1] op_sel_hi:[1,0]
	v_pk_mul_f32 v[142:143], v[142:143], v[0:1] op_sel_hi:[1,0]
	v_mul_f32_e32 v149, 0xbfb8aa3b, v125
	v_mul_f32_e32 v0, 0xbfb8aa3b, v141
	v_mul_f32_e32 v135, 0xbfb8aa3b, v127
	v_mul_f32_e32 v144, 0xbfb8aa3b, v131
	v_mul_f32_e32 v145, 0xbfb8aa3b, v129
	v_mul_f32_e32 v146, 0xbfb8aa3b, v133
	v_mul_f32_e32 v147, 0xbfb8aa3b, v123
	v_mul_f32_e32 v148, 0xbfb8aa3b, v143
	v_exp_f32_e32 v149, v149
	v_exp_f32_e32 v0, v0
	v_exp_f32_e32 v135, v135
	v_exp_f32_e32 v144, v144
	v_exp_f32_e32 v145, v145
	v_exp_f32_e32 v146, v146
	v_exp_f32_e32 v147, v147
	v_exp_f32_e32 v148, v148
	v_add_f32_e32 v149, 1.0, v149
	v_add_f32_e32 v0, 1.0, v0
	v_add_f32_e32 v135, 1.0, v135
	v_add_f32_e32 v144, 1.0, v144
	v_add_f32_e32 v145, 1.0, v145
	v_add_f32_e32 v146, 1.0, v146
	v_add_f32_e32 v147, 1.0, v147
	v_add_f32_e32 v148, 1.0, v148
	v_rcp_f32_e32 v149, v149
	v_rcp_f32_e32 v0, v0
	v_rcp_f32_e32 v135, v135
	v_rcp_f32_e32 v144, v144
	v_rcp_f32_e32 v145, v145
	v_rcp_f32_e32 v146, v146
	v_rcp_f32_e32 v147, v147
	v_rcp_f32_e32 v148, v148
	v_mul_f32_e32 v125, v125, v149
	v_mul_f32_e32 v0, v141, v0
	v_mul_f32_e32 v127, v127, v135
	v_mul_f32_e32 v131, v131, v144
	v_mul_f32_e32 v129, v129, v145
	v_mul_f32_e32 v133, v133, v146
	v_mul_f32_e32 v123, v123, v147
	v_mul_f32_e32 v135, v143, v148
	v_mul_f32_e32 v125, v124, v125
	v_mul_f32_e32 v0, v140, v0
	v_mul_f32_e32 v126, v126, v127
	v_mul_f32_e32 v127, v130, v131
	v_mul_f32_e32 v128, v128, v129
	v_mul_f32_e32 v129, v132, v133
	v_mul_f32_e32 v130, v122, v123
	v_mul_f32_e32 v131, v142, v135
	v_cvt_pk_bf16_f32 v122, v0, v126
	v_cvt_pk_bf16_f32 v123, v127, v128
	v_cvt_pk_bf16_f32 v124, v129, v130
	v_cvt_pk_bf16_f32 v125, v131, v125
	ds_write_b128 v164, v[122:125]
	ds_read_b128 v[168:171], v161
	v_lshl_add_u64 v[172:173], v[138:139], 0, v[166:167]
	s_waitcnt lgkmcnt(0)
	global_store_dwordx4 v[172:173], v[168:171], off
	global_load_dword v0, v[136:137], off offset:64
	s_waitcnt vmcnt(0)
	v_fmamk_f32 v0, v0, 0x3a800000, v237
	v_rsq_f32_e32 v0, v0
	v_mov_b32_e32 v122, v114
	v_mov_b32_e32 v114, v116
	v_mov_b32_e32 v116, v102
	v_mov_b32_e32 v102, v104
	v_or_b32_e32 v104, 16, v134
	v_mov_b32_e32 v123, v110
	v_mov_b32_e32 v110, v115
	v_mov_b32_e32 v115, v112
	v_mov_b32_e32 v112, v117
	v_mov_b32_e32 v117, v106
	v_mov_b32_e32 v106, v103
	v_mov_b32_e32 v103, v108
	v_mov_b32_e32 v108, v105
	v_mad_i64_i32 v[104:105], s[0:1], v104, s74, v[118:119]
	v_lshl_add_u64 v[124:125], v[104:105], 0, v[120:121]
	v_pk_mul_f32 v[104:105], v[122:123], v[0:1] op_sel_hi:[1,0]
	v_pk_mul_f32 v[110:111], v[110:111], v[0:1] op_sel_hi:[1,0]
	v_pk_mul_f32 v[114:115], v[114:115], v[0:1] op_sel_hi:[1,0]
	v_pk_mul_f32 v[112:113], v[112:113], v[0:1] op_sel_hi:[1,0]
	v_pk_mul_f32 v[116:117], v[116:117], v[0:1] op_sel_hi:[1,0]
	v_pk_mul_f32 v[106:107], v[106:107], v[0:1] op_sel_hi:[1,0]
	v_pk_mul_f32 v[102:103], v[102:103], v[0:1] op_sel_hi:[1,0]
	v_pk_mul_f32 v[108:109], v[108:109], v[0:1] op_sel_hi:[1,0]
	v_mul_f32_e32 v0, 0xbfb8aa3b, v105
	v_mul_f32_e32 v122, 0xbfb8aa3b, v111
	v_mul_f32_e32 v123, 0xbfb8aa3b, v115
	v_mul_f32_e32 v126, 0xbfb8aa3b, v113
	v_mul_f32_e32 v127, 0xbfb8aa3b, v117
	v_mul_f32_e32 v128, 0xbfb8aa3b, v107
	v_mul_f32_e32 v129, 0xbfb8aa3b, v103
	v_mul_f32_e32 v130, 0xbfb8aa3b, v109
	v_exp_f32_e32 v0, v0
	v_exp_f32_e32 v122, v122
	v_exp_f32_e32 v123, v123
	v_exp_f32_e32 v126, v126
	v_exp_f32_e32 v127, v127
	v_exp_f32_e32 v128, v128
	v_exp_f32_e32 v129, v129
	v_exp_f32_e32 v130, v130
	v_add_f32_e32 v0, 1.0, v0
	v_add_f32_e32 v122, 1.0, v122
	v_add_f32_e32 v123, 1.0, v123
	v_add_f32_e32 v126, 1.0, v126
	v_add_f32_e32 v127, 1.0, v127
	v_add_f32_e32 v128, 1.0, v128
	v_add_f32_e32 v129, 1.0, v129
	v_add_f32_e32 v130, 1.0, v130
	v_rcp_f32_e32 v0, v0
	v_rcp_f32_e32 v122, v122
	v_rcp_f32_e32 v123, v123
	v_rcp_f32_e32 v126, v126
	v_rcp_f32_e32 v127, v127
	v_rcp_f32_e32 v128, v128
	v_rcp_f32_e32 v129, v129
	v_rcp_f32_e32 v130, v130
	v_mul_f32_e32 v0, v105, v0
	v_mul_f32_e32 v105, v111, v122
	v_mul_f32_e32 v111, v115, v123
	v_mul_f32_e32 v113, v113, v126
	v_mul_f32_e32 v115, v117, v127
	v_mul_f32_e32 v107, v107, v128
	v_mul_f32_e32 v103, v103, v129
	v_mul_f32_e32 v109, v109, v130
	v_mul_f32_e32 v0, v104, v0
	v_mul_f32_e32 v104, v110, v105
	v_mul_f32_e32 v105, v114, v111
	v_mul_f32_e32 v110, v112, v113
	v_mul_f32_e32 v111, v116, v115
	v_mul_f32_e32 v106, v106, v107
	v_mul_f32_e32 v107, v102, v103
	v_mul_f32_e32 v108, v108, v109
	v_cvt_pk_bf16_f32 v102, v0, v104
	v_cvt_pk_bf16_f32 v103, v105, v110
	v_cvt_pk_bf16_f32 v104, v111, v106
	v_cvt_pk_bf16_f32 v105, v107, v108
	ds_write_b128 v164, v[102:105]
	ds_read_b128 v[168:171], v161
	v_lshl_add_u64 v[172:173], v[124:125], 0, v[166:167]
	s_waitcnt lgkmcnt(0)
; __device__ __forceinline__ unsigned cvt_pk_bf16(float lo, float hi) { unsigned r; asm volatile("v_cvt_pk_bf16_f32 %0, %1, %2" : "=v"(r) : "v"(lo), "v"(hi)); return r; }
; __device__ __forceinline__ float sigmoidf_(float x) { return __builtin_amdgcn_rcpf(1.f + __builtin_amdgcn_exp2f(-x * LOG2E)); }
;     __device__ __forceinline__ void operator()(const f32x4 (&acc)[2][2][4][2], const pg8::Unit& u, int wr, int wc, int fr, int fq) const {
;         const int row0 = u.pm * 256 + wr * 64 + fr, col0 = u.pn * 128 + wc * 32 + 8 * fq;
; #pragma unroll
;         for (int ai = 0; ai < 2; ++ai)
; #pragma unroll
;             for (int m = 0; m < 4; ++m) { const int row = row0 + ai * 128 + m * 16; const float rs = __builtin_amdgcn_rsqf(ss[row] * (1.f / DM) + EPS);
;                 float h[8];
; #pragma unroll
;                 for (int n = 0; n < 2; ++n)
; #pragma unroll
;                     for (int j = 0; j < 4; ++j) { const float g = acc[ai][0][m][n][j] * rs, up = acc[ai][1][m][n][j] * rs; h[4 * n + j] = g * sigmoidf_(g) * up; }
;                 u32x4 w; w.x = cvt_pk_bf16(h[0], h[1]); w.y = cvt_pk_bf16(h[2], h[3]); w.z = cvt_pk_bf16(h[4], h[5]); w.w = cvt_pk_bf16(h[6], h[7]);
;                 *(u32x4*)(H + (size_t)row * DFF + col0) = w; }
	global_store_dwordx4 v[172:173], v[168:171], off
	global_load_dword v0, v[136:137], off offset:128
	s_waitcnt vmcnt(0)
	v_fmamk_f32 v0, v0, 0x3a800000, v237
	v_rsq_f32_e32 v0, v0
	v_mov_b32_e32 v102, v98
	v_mov_b32_e32 v98, v100
	v_mov_b32_e32 v100, v86
	v_mov_b32_e32 v86, v88
	v_or_b32_e32 v88, 32, v134
	v_mov_b32_e32 v103, v94
	v_mov_b32_e32 v94, v99
	v_mov_b32_e32 v99, v96
	v_mov_b32_e32 v96, v101
	v_mov_b32_e32 v101, v90
	v_mov_b32_e32 v90, v87
	v_mov_b32_e32 v87, v92
	v_mov_b32_e32 v92, v89
	v_mad_i64_i32 v[88:89], s[0:1], v88, s74, v[118:119]
	v_lshl_add_u64 v[104:105], v[88:89], 0, v[120:121]
	v_pk_mul_f32 v[88:89], v[102:103], v[0:1] op_sel_hi:[1,0]
	v_pk_mul_f32 v[94:95], v[94:95], v[0:1] op_sel_hi:[1,0]
	v_pk_mul_f32 v[98:99], v[98:99], v[0:1] op_sel_hi:[1,0]
	v_pk_mul_f32 v[96:97], v[96:97], v[0:1] op_sel_hi:[1,0]
	v_pk_mul_f32 v[100:101], v[100:101], v[0:1] op_sel_hi:[1,0]
	v_pk_mul_f32 v[90:91], v[90:91], v[0:1] op_sel_hi:[1,0]
	v_pk_mul_f32 v[86:87], v[86:87], v[0:1] op_sel_hi:[1,0]
	v_pk_mul_f32 v[92:93], v[92:93], v[0:1] op_sel_hi:[1,0]
	v_mul_f32_e32 v0, 0xbfb8aa3b, v89
	v_mul_f32_e32 v102, 0xbfb8aa3b, v95
	v_mul_f32_e32 v103, 0xbfb8aa3b, v99
	v_mul_f32_e32 v106, 0xbfb8aa3b, v97
	v_mul_f32_e32 v107, 0xbfb8aa3b, v101
	v_mul_f32_e32 v108, 0xbfb8aa3b, v91
	v_mul_f32_e32 v109, 0xbfb8aa3b, v87
	v_mul_f32_e32 v110, 0xbfb8aa3b, v93
	v_exp_f32_e32 v0, v0
	v_exp_f32_e32 v102, v102
	v_exp_f32_e32 v103, v103
	v_exp_f32_e32 v106, v106
	v_exp_f32_e32 v107, v107
	v_exp_f32_e32 v108, v108
	v_exp_f32_e32 v109, v109
	v_exp_f32_e32 v110, v110
	v_add_f32_e32 v0, 1.0, v0
	v_add_f32_e32 v102, 1.0, v102
	v_add_f32_e32 v103, 1.0, v103
	v_add_f32_e32 v106, 1.0, v106
	v_add_f32_e32 v107, 1.0, v107
	v_add_f32_e32 v108, 1.0, v108
	v_add_f32_e32 v109, 1.0, v109
	v_add_f32_e32 v110, 1.0, v110
	v_rcp_f32_e32 v0, v0
	v_rcp_f32_e32 v102, v102
	v_rcp_f32_e32 v103, v103
	v_rcp_f32_e32 v106, v106
	v_rcp_f32_e32 v107, v107
	v_rcp_f32_e32 v108, v108
	v_rcp_f32_e32 v109, v109
	v_rcp_f32_e32 v110, v110
	v_mul_f32_e32 v0, v89, v0
	v_mul_f32_e32 v89, v95, v102
	v_mul_f32_e32 v95, v99, v103
	v_mul_f32_e32 v97, v97, v106
	v_mul_f32_e32 v99, v101, v107
	v_mul_f32_e32 v91, v91, v108
	v_mul_f32_e32 v87, v87, v109
	v_mul_f32_e32 v93, v93, v110
	v_mul_f32_e32 v0, v88, v0
	v_mul_f32_e32 v88, v94, v89
	v_mul_f32_e32 v89, v98, v95
	v_mul_f32_e32 v94, v96, v97
	v_mul_f32_e32 v95, v100, v99
	v_mul_f32_e32 v90, v90, v91
	v_mul_f32_e32 v91, v86, v87
	v_mul_f32_e32 v92, v92, v93
	v_cvt_pk_bf16_f32 v86, v0, v88
	v_cvt_pk_bf16_f32 v87, v89, v94
	v_cvt_pk_bf16_f32 v88, v95, v90
	v_cvt_pk_bf16_f32 v89, v91, v92
	ds_write_b128 v164, v[86:89]
	ds_read_b128 v[168:171], v161
	v_lshl_add_u64 v[172:173], v[104:105], 0, v[166:167]
	s_waitcnt lgkmcnt(0)
	global_store_dwordx4 v[172:173], v[168:171], off
	global_load_dword v0, v[136:137], off offset:192
	s_waitcnt vmcnt(0)
	v_fmamk_f32 v0, v0, 0x3a800000, v237
	v_rsq_f32_e32 v0, v0
	v_mov_b32_e32 v86, v82
	v_mov_b32_e32 v82, v84
	v_mov_b32_e32 v84, v70
	v_mov_b32_e32 v70, v72
	v_or_b32_e32 v72, 48, v134
	v_mov_b32_e32 v87, v78
	v_mov_b32_e32 v78, v83
	v_mov_b32_e32 v83, v80
	v_mov_b32_e32 v80, v85
	v_mov_b32_e32 v85, v74
	v_mov_b32_e32 v74, v71
	v_mov_b32_e32 v71, v76
	v_mov_b32_e32 v76, v73
	v_mad_i64_i32 v[72:73], s[0:1], v72, s74, v[118:119]
	v_lshl_add_u64 v[88:89], v[72:73], 0, v[120:121]
	v_pk_mul_f32 v[72:73], v[86:87], v[0:1] op_sel_hi:[1,0]
	v_pk_mul_f32 v[78:79], v[78:79], v[0:1] op_sel_hi:[1,0]
	v_pk_mul_f32 v[82:83], v[82:83], v[0:1] op_sel_hi:[1,0]
	v_pk_mul_f32 v[80:81], v[80:81], v[0:1] op_sel_hi:[1,0]
	v_pk_mul_f32 v[84:85], v[84:85], v[0:1] op_sel_hi:[1,0]
	v_pk_mul_f32 v[74:75], v[74:75], v[0:1] op_sel_hi:[1,0]
	v_pk_mul_f32 v[70:71], v[70:71], v[0:1] op_sel_hi:[1,0]
	v_pk_mul_f32 v[76:77], v[76:77], v[0:1] op_sel_hi:[1,0]
	v_mul_f32_e32 v0, 0xbfb8aa3b, v73
	v_mul_f32_e32 v86, 0xbfb8aa3b, v79
	v_mul_f32_e32 v87, 0xbfb8aa3b, v83
	v_mul_f32_e32 v90, 0xbfb8aa3b, v81
	v_mul_f32_e32 v91, 0xbfb8aa3b, v85
	v_mul_f32_e32 v92, 0xbfb8aa3b, v75
	v_mul_f32_e32 v93, 0xbfb8aa3b, v71
	v_mul_f32_e32 v94, 0xbfb8aa3b, v77
	v_exp_f32_e32 v0, v0
	v_exp_f32_e32 v86, v86
	v_exp_f32_e32 v87, v87
	v_exp_f32_e32 v90, v90
	v_exp_f32_e32 v91, v91
	v_exp_f32_e32 v92, v92
	v_exp_f32_e32 v93, v93
	v_exp_f32_e32 v94, v94
	v_add_f32_e32 v0, 1.0, v0
	v_add_f32_e32 v86, 1.0, v86
	v_add_f32_e32 v87, 1.0, v87
	v_add_f32_e32 v90, 1.0, v90
	v_add_f32_e32 v91, 1.0, v91
	v_add_f32_e32 v92, 1.0, v92
	v_add_f32_e32 v93, 1.0, v93
	v_add_f32_e32 v94, 1.0, v94
	v_rcp_f32_e32 v0, v0
	v_rcp_f32_e32 v86, v86
	v_rcp_f32_e32 v87, v87
	v_rcp_f32_e32 v90, v90
	v_rcp_f32_e32 v91, v91
	v_rcp_f32_e32 v92, v92
	v_rcp_f32_e32 v93, v93
	v_rcp_f32_e32 v94, v94
	v_mul_f32_e32 v0, v73, v0
	v_mul_f32_e32 v73, v79, v86
	v_mul_f32_e32 v79, v83, v87
	v_mul_f32_e32 v81, v81, v90
	v_mul_f32_e32 v83, v85, v91
	v_mul_f32_e32 v75, v75, v92
	v_mul_f32_e32 v71, v71, v93
	v_mul_f32_e32 v77, v77, v94
	v_mul_f32_e32 v0, v72, v0
	v_mul_f32_e32 v72, v78, v73
	v_mul_f32_e32 v73, v82, v79
	v_mul_f32_e32 v78, v80, v81
	v_mul_f32_e32 v79, v84, v83
	v_mul_f32_e32 v74, v74, v75
	v_mul_f32_e32 v75, v70, v71
	v_mul_f32_e32 v76, v76, v77
	v_cvt_pk_bf16_f32 v70, v0, v72
	v_cvt_pk_bf16_f32 v71, v73, v78
	v_cvt_pk_bf16_f32 v72, v79, v74
	v_cvt_pk_bf16_f32 v73, v75, v76
	ds_write_b128 v164, v[70:73]
	ds_read_b128 v[168:171], v161
	v_lshl_add_u64 v[172:173], v[88:89], 0, v[166:167]
	s_waitcnt lgkmcnt(0)
	global_store_dwordx4 v[172:173], v[168:171], off
	global_load_dword v0, v[136:137], off offset:512
	s_waitcnt vmcnt(0)
; __device__ __forceinline__ unsigned cvt_pk_bf16(float lo, float hi) { unsigned r; asm volatile("v_cvt_pk_bf16_f32 %0, %1, %2" : "=v"(r) : "v"(lo), "v"(hi)); return r; }
; __device__ __forceinline__ float sigmoidf_(float x) { return __builtin_amdgcn_rcpf(1.f + __builtin_amdgcn_exp2f(-x * LOG2E)); }
;     __device__ __forceinline__ void operator()(const f32x4 (&acc)[2][2][4][2], const pg8::Unit& u, int wr, int wc, int fr, int fq) const {
;         const int row0 = u.pm * 256 + wr * 64 + fr, col0 = u.pn * 128 + wc * 32 + 8 * fq;
; #pragma unroll
;         for (int ai = 0; ai < 2; ++ai)
; #pragma unroll
;             for (int m = 0; m < 4; ++m) { const int row = row0 + ai * 128 + m * 16; const float rs = __builtin_amdgcn_rsqf(ss[row] * (1.f / DM) + EPS);
;                 float h[8];
; #pragma unroll
;                 for (int n = 0; n < 2; ++n)
; #pragma unroll
;                     for (int j = 0; j < 4; ++j) { const float g = acc[ai][0][m][n][j] * rs, up = acc[ai][1][m][n][j] * rs; h[4 * n + j] = g * sigmoidf_(g) * up; }
;                 u32x4 w; w.x = cvt_pk_bf16(h[0], h[1]); w.y = cvt_pk_bf16(h[2], h[3]); w.z = cvt_pk_bf16(h[4], h[5]); w.w = cvt_pk_bf16(h[6], h[7]);
;                 *(u32x4*)(H + (size_t)row * DFF + col0) = w; }
	v_fmamk_f32 v0, v0, 0x3a800000, v237
	v_rsq_f32_e32 v0, v0
	v_mov_b32_e32 v70, v66
	v_mov_b32_e32 v66, v68
	v_mov_b32_e32 v68, v54
	v_mov_b32_e32 v54, v56
	v_add_u32_e32 v56, 0x80, v134
	v_mov_b32_e32 v71, v62
	v_mov_b32_e32 v62, v67
	v_mov_b32_e32 v67, v64
	v_mov_b32_e32 v64, v69
	v_mov_b32_e32 v69, v58
	v_mov_b32_e32 v58, v55
	v_mov_b32_e32 v55, v60
	v_mov_b32_e32 v60, v57
	v_mad_i64_i32 v[56:57], s[0:1], v56, s74, v[118:119]
	v_lshl_add_u64 v[72:73], v[56:57], 0, v[120:121]
	v_pk_mul_f32 v[56:57], v[70:71], v[0:1] op_sel_hi:[1,0]
	v_pk_mul_f32 v[62:63], v[62:63], v[0:1] op_sel_hi:[1,0]
	v_pk_mul_f32 v[66:67], v[66:67], v[0:1] op_sel_hi:[1,0]
	v_pk_mul_f32 v[64:65], v[64:65], v[0:1] op_sel_hi:[1,0]
	v_pk_mul_f32 v[68:69], v[68:69], v[0:1] op_sel_hi:[1,0]
	v_pk_mul_f32 v[58:59], v[58:59], v[0:1] op_sel_hi:[1,0]
	v_pk_mul_f32 v[54:55], v[54:55], v[0:1] op_sel_hi:[1,0]
	v_pk_mul_f32 v[60:61], v[60:61], v[0:1] op_sel_hi:[1,0]
	v_mul_f32_e32 v0, 0xbfb8aa3b, v57
	v_mul_f32_e32 v70, 0xbfb8aa3b, v63
	v_mul_f32_e32 v71, 0xbfb8aa3b, v67
	v_mul_f32_e32 v74, 0xbfb8aa3b, v65
	v_mul_f32_e32 v75, 0xbfb8aa3b, v69
	v_mul_f32_e32 v76, 0xbfb8aa3b, v59
	v_mul_f32_e32 v77, 0xbfb8aa3b, v55
	v_mul_f32_e32 v78, 0xbfb8aa3b, v61
	v_exp_f32_e32 v0, v0
	v_exp_f32_e32 v70, v70
	v_exp_f32_e32 v71, v71
	v_exp_f32_e32 v74, v74
	v_exp_f32_e32 v75, v75
	v_exp_f32_e32 v76, v76
	v_exp_f32_e32 v77, v77
	v_exp_f32_e32 v78, v78
	v_add_f32_e32 v0, 1.0, v0
	v_add_f32_e32 v70, 1.0, v70
	v_add_f32_e32 v71, 1.0, v71
	v_add_f32_e32 v74, 1.0, v74
	v_add_f32_e32 v75, 1.0, v75
	v_add_f32_e32 v76, 1.0, v76
	v_add_f32_e32 v77, 1.0, v77
	v_add_f32_e32 v78, 1.0, v78
	v_rcp_f32_e32 v0, v0
	v_rcp_f32_e32 v70, v70
	v_rcp_f32_e32 v71, v71
	v_rcp_f32_e32 v74, v74
	v_rcp_f32_e32 v75, v75
	v_rcp_f32_e32 v76, v76
	v_rcp_f32_e32 v77, v77
	v_rcp_f32_e32 v78, v78
	v_mul_f32_e32 v0, v57, v0
	v_mul_f32_e32 v57, v63, v70
	v_mul_f32_e32 v63, v67, v71
	v_mul_f32_e32 v65, v65, v74
	v_mul_f32_e32 v67, v69, v75
	v_mul_f32_e32 v59, v59, v76
	v_mul_f32_e32 v55, v55, v77
	v_mul_f32_e32 v61, v61, v78
	v_mul_f32_e32 v0, v56, v0
	v_mul_f32_e32 v56, v62, v57
	v_mul_f32_e32 v57, v66, v63
	v_mul_f32_e32 v62, v64, v65
	v_mul_f32_e32 v63, v68, v67
	v_mul_f32_e32 v58, v58, v59
	v_mul_f32_e32 v59, v54, v55
	v_mul_f32_e32 v60, v60, v61
	v_cvt_pk_bf16_f32 v54, v0, v56
	v_cvt_pk_bf16_f32 v55, v57, v62
	v_cvt_pk_bf16_f32 v56, v63, v58
	v_cvt_pk_bf16_f32 v57, v59, v60
	ds_write_b128 v164, v[54:57]
	ds_read_b128 v[168:171], v161
	v_lshl_add_u64 v[172:173], v[72:73], 0, v[166:167]
	s_waitcnt lgkmcnt(0)
	global_store_dwordx4 v[172:173], v[168:171], off
	global_load_dword v0, v[136:137], off offset:576
	s_waitcnt vmcnt(0)
	v_fmamk_f32 v0, v0, 0x3a800000, v237
	v_rsq_f32_e32 v0, v0
	v_mov_b32_e32 v54, v50
	v_mov_b32_e32 v50, v52
	v_mov_b32_e32 v52, v38
	v_mov_b32_e32 v38, v40
	v_add_u32_e32 v40, 0x90, v134
	v_mov_b32_e32 v55, v46
	v_mov_b32_e32 v46, v51
	v_mov_b32_e32 v51, v48
	v_mov_b32_e32 v48, v53
	v_mov_b32_e32 v53, v42
	v_mov_b32_e32 v42, v39
	v_mov_b32_e32 v39, v44
	v_mov_b32_e32 v44, v41
	v_mad_i64_i32 v[40:41], s[0:1], v40, s74, v[118:119]
	v_lshl_add_u64 v[56:57], v[40:41], 0, v[120:121]
	v_pk_mul_f32 v[40:41], v[54:55], v[0:1] op_sel_hi:[1,0]
	v_pk_mul_f32 v[46:47], v[46:47], v[0:1] op_sel_hi:[1,0]
	v_pk_mul_f32 v[50:51], v[50:51], v[0:1] op_sel_hi:[1,0]
	v_pk_mul_f32 v[48:49], v[48:49], v[0:1] op_sel_hi:[1,0]
	v_pk_mul_f32 v[52:53], v[52:53], v[0:1] op_sel_hi:[1,0]
	v_pk_mul_f32 v[42:43], v[42:43], v[0:1] op_sel_hi:[1,0]
	v_pk_mul_f32 v[38:39], v[38:39], v[0:1] op_sel_hi:[1,0]
	v_pk_mul_f32 v[44:45], v[44:45], v[0:1] op_sel_hi:[1,0]
	v_mul_f32_e32 v0, 0xbfb8aa3b, v41
	v_mul_f32_e32 v54, 0xbfb8aa3b, v47
	v_mul_f32_e32 v55, 0xbfb8aa3b, v51
	v_mul_f32_e32 v58, 0xbfb8aa3b, v49
	v_mul_f32_e32 v59, 0xbfb8aa3b, v53
	v_mul_f32_e32 v60, 0xbfb8aa3b, v43
	v_mul_f32_e32 v61, 0xbfb8aa3b, v39
	v_mul_f32_e32 v62, 0xbfb8aa3b, v45
	v_exp_f32_e32 v0, v0
	v_exp_f32_e32 v54, v54
	v_exp_f32_e32 v55, v55
	v_exp_f32_e32 v58, v58
	v_exp_f32_e32 v59, v59
	v_exp_f32_e32 v60, v60
	v_exp_f32_e32 v61, v61
	v_exp_f32_e32 v62, v62
	v_add_f32_e32 v0, 1.0, v0
	v_add_f32_e32 v54, 1.0, v54
	v_add_f32_e32 v55, 1.0, v55
	v_add_f32_e32 v58, 1.0, v58
	v_add_f32_e32 v59, 1.0, v59
	v_add_f32_e32 v60, 1.0, v60
	v_add_f32_e32 v61, 1.0, v61
	v_add_f32_e32 v62, 1.0, v62
	v_rcp_f32_e32 v0, v0
	v_rcp_f32_e32 v54, v54
	v_rcp_f32_e32 v55, v55
	v_rcp_f32_e32 v58, v58
	v_rcp_f32_e32 v59, v59
	v_rcp_f32_e32 v60, v60
	v_rcp_f32_e32 v61, v61
	v_rcp_f32_e32 v62, v62
	v_mul_f32_e32 v0, v41, v0
	v_mul_f32_e32 v41, v47, v54
	v_mul_f32_e32 v47, v51, v55
	v_mul_f32_e32 v49, v49, v58
	v_mul_f32_e32 v51, v53, v59
	v_mul_f32_e32 v43, v43, v60
	v_mul_f32_e32 v39, v39, v61
	v_mul_f32_e32 v45, v45, v62
	v_mul_f32_e32 v0, v40, v0
	v_mul_f32_e32 v40, v46, v41
	v_mul_f32_e32 v41, v50, v47
	v_mul_f32_e32 v46, v48, v49
	v_mul_f32_e32 v47, v52, v51
	v_mul_f32_e32 v42, v42, v43
	v_mul_f32_e32 v43, v38, v39
	v_mul_f32_e32 v44, v44, v45
	v_cvt_pk_bf16_f32 v38, v0, v40
	v_cvt_pk_bf16_f32 v39, v41, v46
	v_cvt_pk_bf16_f32 v40, v47, v42
	v_cvt_pk_bf16_f32 v41, v43, v44
	ds_write_b128 v164, v[38:41]
	ds_read_b128 v[168:171], v161
	v_lshl_add_u64 v[172:173], v[56:57], 0, v[166:167]
	s_waitcnt lgkmcnt(0)
	global_store_dwordx4 v[172:173], v[168:171], off
	global_load_dword v0, v[136:137], off offset:640
	s_waitcnt vmcnt(0)
; __device__ __forceinline__ unsigned cvt_pk_bf16(float lo, float hi) { unsigned r; asm volatile("v_cvt_pk_bf16_f32 %0, %1, %2" : "=v"(r) : "v"(lo), "v"(hi)); return r; }
; __device__ __forceinline__ float sigmoidf_(float x) { return __builtin_amdgcn_rcpf(1.f + __builtin_amdgcn_exp2f(-x * LOG2E)); }
;     __device__ __forceinline__ void operator()(const f32x4 (&acc)[2][2][4][2], const pg8::Unit& u, int wr, int wc, int fr, int fq) const {
;         const int row0 = u.pm * 256 + wr * 64 + fr, col0 = u.pn * 128 + wc * 32 + 8 * fq;
; #pragma unroll
;         for (int ai = 0; ai < 2; ++ai)
; #pragma unroll
;             for (int m = 0; m < 4; ++m) { const int row = row0 + ai * 128 + m * 16; const float rs = __builtin_amdgcn_rsqf(ss[row] * (1.f / DM) + EPS);
;                 float h[8];
; #pragma unroll
;                 for (int n = 0; n < 2; ++n)
; #pragma unroll
;                     for (int j = 0; j < 4; ++j) { const float g = acc[ai][0][m][n][j] * rs, up = acc[ai][1][m][n][j] * rs; h[4 * n + j] = g * sigmoidf_(g) * up; }
;                 u32x4 w; w.x = cvt_pk_bf16(h[0], h[1]); w.y = cvt_pk_bf16(h[2], h[3]); w.z = cvt_pk_bf16(h[4], h[5]); w.w = cvt_pk_bf16(h[6], h[7]);
;                 *(u32x4*)(H + (size_t)row * DFF + col0) = w; }
	v_fmamk_f32 v0, v0, 0x3a800000, v237
	v_rsq_f32_e32 v0, v0
	v_mov_b32_e32 v38, v34
	v_mov_b32_e32 v34, v36
	v_mov_b32_e32 v36, v22
	v_mov_b32_e32 v22, v24
	v_add_u32_e32 v24, 0xa0, v134
	v_mov_b32_e32 v39, v30
	v_mov_b32_e32 v30, v35
	v_mov_b32_e32 v35, v32
	v_mov_b32_e32 v32, v37
	v_mov_b32_e32 v37, v26
	v_mov_b32_e32 v26, v23
	v_mov_b32_e32 v23, v28
	v_mov_b32_e32 v28, v25
	v_mad_i64_i32 v[24:25], s[0:1], v24, s74, v[118:119]
	v_lshl_add_u64 v[40:41], v[24:25], 0, v[120:121]
	v_pk_mul_f32 v[24:25], v[38:39], v[0:1] op_sel_hi:[1,0]
	v_pk_mul_f32 v[30:31], v[30:31], v[0:1] op_sel_hi:[1,0]
	v_pk_mul_f32 v[34:35], v[34:35], v[0:1] op_sel_hi:[1,0]
	v_pk_mul_f32 v[32:33], v[32:33], v[0:1] op_sel_hi:[1,0]
	v_pk_mul_f32 v[36:37], v[36:37], v[0:1] op_sel_hi:[1,0]
	v_pk_mul_f32 v[26:27], v[26:27], v[0:1] op_sel_hi:[1,0]
	v_pk_mul_f32 v[22:23], v[22:23], v[0:1] op_sel_hi:[1,0]
	v_pk_mul_f32 v[28:29], v[28:29], v[0:1] op_sel_hi:[1,0]
	v_mul_f32_e32 v0, 0xbfb8aa3b, v25
	v_mul_f32_e32 v38, 0xbfb8aa3b, v31
	v_mul_f32_e32 v39, 0xbfb8aa3b, v35
	v_mul_f32_e32 v42, 0xbfb8aa3b, v33
	v_mul_f32_e32 v43, 0xbfb8aa3b, v37
	v_mul_f32_e32 v44, 0xbfb8aa3b, v27
	v_mul_f32_e32 v45, 0xbfb8aa3b, v23
	v_mul_f32_e32 v46, 0xbfb8aa3b, v29
	v_exp_f32_e32 v0, v0
	v_exp_f32_e32 v38, v38
	v_exp_f32_e32 v39, v39
	v_exp_f32_e32 v42, v42
	v_exp_f32_e32 v43, v43
	v_exp_f32_e32 v44, v44
	v_exp_f32_e32 v45, v45
	v_exp_f32_e32 v46, v46
	v_add_f32_e32 v0, 1.0, v0
	v_add_f32_e32 v38, 1.0, v38
	v_add_f32_e32 v39, 1.0, v39
	v_add_f32_e32 v42, 1.0, v42
	v_add_f32_e32 v43, 1.0, v43
	v_add_f32_e32 v44, 1.0, v44
	v_add_f32_e32 v45, 1.0, v45
	v_add_f32_e32 v46, 1.0, v46
	v_rcp_f32_e32 v0, v0
	v_rcp_f32_e32 v38, v38
	v_rcp_f32_e32 v39, v39
	v_rcp_f32_e32 v42, v42
	v_rcp_f32_e32 v43, v43
	v_rcp_f32_e32 v44, v44
	v_rcp_f32_e32 v45, v45
	v_rcp_f32_e32 v46, v46
	v_mul_f32_e32 v0, v25, v0
	v_mul_f32_e32 v25, v31, v38
	v_mul_f32_e32 v31, v35, v39
	v_mul_f32_e32 v33, v33, v42
	v_mul_f32_e32 v35, v37, v43
	v_mul_f32_e32 v27, v27, v44
	v_mul_f32_e32 v23, v23, v45
	v_mul_f32_e32 v29, v29, v46
	v_mul_f32_e32 v0, v24, v0
	v_mul_f32_e32 v24, v30, v25
	v_mul_f32_e32 v25, v34, v31
	v_mul_f32_e32 v30, v32, v33
	v_mul_f32_e32 v31, v36, v35
	v_mul_f32_e32 v26, v26, v27
	v_mul_f32_e32 v27, v22, v23
	v_mul_f32_e32 v28, v28, v29
	v_cvt_pk_bf16_f32 v22, v0, v24
	v_cvt_pk_bf16_f32 v23, v25, v30
	v_cvt_pk_bf16_f32 v24, v31, v26
	v_cvt_pk_bf16_f32 v25, v27, v28
	ds_write_b128 v164, v[22:25]
	ds_read_b128 v[168:171], v161
	v_lshl_add_u64 v[172:173], v[40:41], 0, v[166:167]
	s_waitcnt lgkmcnt(0)
	global_store_dwordx4 v[172:173], v[168:171], off
	global_load_dword v0, v[136:137], off offset:704
	s_waitcnt vmcnt(0)
	v_fmamk_f32 v0, v0, 0x3a800000, v237
	v_rsq_f32_e32 v0, v0
	v_mov_b32_e32 v22, v18
	v_mov_b32_e32 v18, v20
	v_mov_b32_e32 v20, v6
	v_mov_b32_e32 v6, v8
	v_add_u32_e32 v8, 0xb0, v134
	v_mov_b32_e32 v23, v14
	v_mov_b32_e32 v14, v19
	v_mov_b32_e32 v19, v16
	v_mov_b32_e32 v16, v21
	v_mov_b32_e32 v21, v10
	v_mov_b32_e32 v10, v7
	v_mov_b32_e32 v7, v12
	v_mov_b32_e32 v12, v9
	v_mad_i64_i32 v[8:9], s[0:1], v8, s74, v[118:119]
	v_lshl_add_u64 v[24:25], v[8:9], 0, v[120:121]
	v_pk_mul_f32 v[8:9], v[22:23], v[0:1] op_sel_hi:[1,0]
	v_pk_mul_f32 v[14:15], v[14:15], v[0:1] op_sel_hi:[1,0]
	v_pk_mul_f32 v[18:19], v[18:19], v[0:1] op_sel_hi:[1,0]
	v_pk_mul_f32 v[16:17], v[16:17], v[0:1] op_sel_hi:[1,0]
	v_pk_mul_f32 v[20:21], v[20:21], v[0:1] op_sel_hi:[1,0]
	v_pk_mul_f32 v[10:11], v[10:11], v[0:1] op_sel_hi:[1,0]
	v_pk_mul_f32 v[6:7], v[6:7], v[0:1] op_sel_hi:[1,0]
	v_pk_mul_f32 v[12:13], v[12:13], v[0:1] op_sel_hi:[1,0]
	v_mul_f32_e32 v0, 0xbfb8aa3b, v9
	v_mul_f32_e32 v22, 0xbfb8aa3b, v15
	v_mul_f32_e32 v23, 0xbfb8aa3b, v19
	v_mul_f32_e32 v26, 0xbfb8aa3b, v17
	v_mul_f32_e32 v27, 0xbfb8aa3b, v21
	v_mul_f32_e32 v28, 0xbfb8aa3b, v11
	v_mul_f32_e32 v29, 0xbfb8aa3b, v7
	v_mul_f32_e32 v30, 0xbfb8aa3b, v13
	v_exp_f32_e32 v0, v0
	v_exp_f32_e32 v22, v22
	v_exp_f32_e32 v23, v23
	v_exp_f32_e32 v26, v26
	v_exp_f32_e32 v27, v27
	v_exp_f32_e32 v28, v28
	v_exp_f32_e32 v29, v29
	v_exp_f32_e32 v30, v30
	v_add_f32_e32 v0, 1.0, v0
	v_add_f32_e32 v22, 1.0, v22
	v_add_f32_e32 v23, 1.0, v23
	v_add_f32_e32 v26, 1.0, v26
	v_add_f32_e32 v27, 1.0, v27
	v_add_f32_e32 v28, 1.0, v28
	v_add_f32_e32 v29, 1.0, v29
	v_add_f32_e32 v30, 1.0, v30
	v_rcp_f32_e32 v0, v0
	v_rcp_f32_e32 v22, v22
	v_rcp_f32_e32 v23, v23
	v_rcp_f32_e32 v26, v26
	v_rcp_f32_e32 v27, v27
	v_rcp_f32_e32 v28, v28
	v_rcp_f32_e32 v29, v29
	v_rcp_f32_e32 v30, v30
	v_mul_f32_e32 v0, v9, v0
	v_mul_f32_e32 v9, v15, v22
	v_mul_f32_e32 v15, v19, v23
	v_mul_f32_e32 v17, v17, v26
	v_mul_f32_e32 v19, v21, v27
	v_mul_f32_e32 v11, v11, v28
	v_mul_f32_e32 v7, v7, v29
	v_mul_f32_e32 v13, v13, v30
	v_mul_f32_e32 v0, v8, v0
	v_mul_f32_e32 v8, v14, v9
	v_mul_f32_e32 v9, v18, v15
	s_mov_b64 s[0:1], -1
	v_mul_f32_e32 v14, v16, v17
	v_mul_f32_e32 v15, v20, v19
	v_mul_f32_e32 v10, v10, v11
	v_mul_f32_e32 v11, v6, v7
	v_mul_f32_e32 v12, v12, v13
	v_cvt_pk_bf16_f32 v6, v0, v8
	v_cvt_pk_bf16_f32 v7, v9, v14
	v_cvt_pk_bf16_f32 v8, v15, v10
	v_cvt_pk_bf16_f32 v9, v11, v12
	ds_write_b128 v164, v[6:9]
	ds_read_b128 v[168:171], v161
	v_lshl_add_u64 v[172:173], v[24:25], 0, v[166:167]
	s_waitcnt lgkmcnt(0)
	global_store_dwordx4 v[172:173], v[168:171], off
	s_cbranch_vccnz .LBB0_262
	s_andn2_b64 vcc, exec, s[16:17]
	s_cbranch_vccnz .LBB0_261
	s_barrier

; __device__ __forceinline__ unsigned cvt_pk_bf16(float lo, float hi) { unsigned r; asm volatile("v_cvt_pk_bf16_f32 %0, %1, %2" : "=v"(r) : "v"(lo), "v"(hi)); return r; }
; __device__ __forceinline__ float sigmoidf_(float x) { return __builtin_amdgcn_rcpf(1.f + __builtin_amdgcn_exp2f(-x * LOG2E)); }
;     __device__ __forceinline__ void operator()(const f32x4 (&acc)[2][2][4][2], const pg8::Unit& u, int wr, int wc, int fr, int fq) const {
;         const int row0 = u.pm * 256 + wr * 64 + fr, col0 = u.pn * 128 + wc * 32 + 8 * fq;
; #pragma unroll
;         for (int ai = 0; ai < 2; ++ai)
; #pragma unroll
;             for (int m = 0; m < 4; ++m) { const int row = row0 + ai * 128 + m * 16; const float rs = __builtin_amdgcn_rsqf(ss[row] * (1.f / DM) + EPS);
;                 float h[8];
; #pragma unroll
;                 for (int n = 0; n < 2; ++n)
; #pragma unroll
;                     for (int j = 0; j < 4; ++j) { const float g = acc[ai][0][m][n][j] * rs, up = acc[ai][1][m][n][j] * rs; h[4 * n + j] = g * sigmoidf_(g) * up; }
;                 u32x4 w; w.x = cvt_pk_bf16(h[0], h[1]); w.y = cvt_pk_bf16(h[2], h[3]); w.z = cvt_pk_bf16(h[4], h[5]); w.w = cvt_pk_bf16(h[6], h[7]);
;                 *(u32x4*)(H + (size_t)row * DFF + col0) = w; }
.LBB0_1197:
	v_mbcnt_lo_u32_b32 v160, -1, 0
	v_mbcnt_hi_u32_b32 v160, -1, v160
	s_lshl_b32 s101, s96, 10
	s_add_u32 s101, s101, 0x20100
	v_lshlrev_b32_e32 v161, 4, v160
	v_add_u32_e32 v161, s101, v161
	v_and_b32_e32 v162, 15, v160
	v_lshrrev_b32_e32 v163, 4, v160
	v_lshlrev_b32_e32 v164, 6, v162
	v_lshl_add_u32 v164, v163, 4, v164
	v_add_u32_e32 v164, s101, v164
	v_lshrrev_b32_e32 v165, 2, v160
	v_sub_u32_e32 v165, v165, v162
	v_mul_i32_i24_e32 v165, 0x1600, v165
	v_and_b32_e32 v167, 3, v160
	v_sub_u32_e32 v167, v167, v163
	v_lshl_add_u32 v166, v167, 4, v165
	v_ashrrev_i32_e32 v167, 31, v166
	v_lshl_add_u32 v134, s34, 8, v232
	v_ashrrev_i32_e32 v135, 31, v134
	v_lshl_add_u64 v[136:137], v[134:135], 2, s[14:15]
	global_load_dword v0, v[136:137], off
	v_lshl_or_b32 v138, s30, 7, v234
	v_mov_b32_e32 v143, v120
	v_mov_b32_e32 v120, v125
	v_mov_b32_e32 v140, v130
	v_mov_b32_e32 v141, v126
	v_mov_b32_e32 v126, v131
	v_mov_b32_e32 v130, v132
	v_mov_b32_e32 v131, v128
	v_mov_b32_e32 v128, v133
	v_mov_b32_e32 v132, v122
	v_mov_b32_e32 v133, v118
	v_mov_b32_e32 v118, v123
	v_mov_b32_e32 v142, v124
	v_mov_b64_e32 v[122:123], s[12:13]
	v_ashrrev_i32_e32 v139, 31, v138
	v_or_b32_e32 v146, 16, v134
	v_mad_i64_i32 v[144:145], s[0:1], v134, s68, v[122:123]
	v_lshlrev_b64 v[124:125], 1, v[138:139]
	v_ashrrev_i32_e32 v147, 31, v146
	v_lshl_add_u64 v[138:139], v[144:145], 0, v[124:125]
	v_lshl_add_u64 v[144:145], v[146:147], 2, s[14:15]
	s_andn2_b64 vcc, exec, s[8:9]
	s_waitcnt vmcnt(0)
	v_fmamk_f32 v0, v0, 0x3a800000, v236
	v_rsq_f32_e32 v0, v0
	s_nop 0
	v_pk_mul_f32 v[120:121], v[120:121], v[0:1] op_sel_hi:[1,0]
	v_pk_mul_f32 v[140:141], v[140:141], v[0:1] op_sel_hi:[1,0]
	v_pk_mul_f32 v[126:127], v[126:127], v[0:1] op_sel_hi:[1,0]
	v_pk_mul_f32 v[130:131], v[130:131], v[0:1] op_sel_hi:[1,0]
	v_pk_mul_f32 v[128:129], v[128:129], v[0:1] op_sel_hi:[1,0]
	v_pk_mul_f32 v[132:133], v[132:133], v[0:1] op_sel_hi:[1,0]
	v_pk_mul_f32 v[118:119], v[118:119], v[0:1] op_sel_hi:[1,0]
	v_pk_mul_f32 v[142:143], v[142:143], v[0:1] op_sel_hi:[1,0]
	v_mul_f32_e32 v152, 0xbfb8aa3b, v121
	v_mul_f32_e32 v0, 0xbfb8aa3b, v141
	v_mul_f32_e32 v135, 0xbfb8aa3b, v127
	v_mul_f32_e32 v147, 0xbfb8aa3b, v131
	v_mul_f32_e32 v148, 0xbfb8aa3b, v129
	v_mul_f32_e32 v149, 0xbfb8aa3b, v133
	v_mul_f32_e32 v150, 0xbfb8aa3b, v119
	v_mul_f32_e32 v151, 0xbfb8aa3b, v143
	v_exp_f32_e32 v152, v152
	v_exp_f32_e32 v0, v0
	v_exp_f32_e32 v135, v135
	v_exp_f32_e32 v147, v147
	v_exp_f32_e32 v148, v148
	v_exp_f32_e32 v149, v149
	v_exp_f32_e32 v150, v150
	v_exp_f32_e32 v151, v151
	v_add_f32_e32 v152, 1.0, v152
	v_add_f32_e32 v0, 1.0, v0
	v_add_f32_e32 v135, 1.0, v135
	v_add_f32_e32 v147, 1.0, v147
	v_add_f32_e32 v148, 1.0, v148
	v_add_f32_e32 v149, 1.0, v149
	v_add_f32_e32 v150, 1.0, v150
	v_add_f32_e32 v151, 1.0, v151
	v_rcp_f32_e32 v152, v152
	v_rcp_f32_e32 v0, v0
	v_rcp_f32_e32 v135, v135
	v_rcp_f32_e32 v147, v147
	v_rcp_f32_e32 v148, v148
	v_rcp_f32_e32 v149, v149
	v_rcp_f32_e32 v150, v150
	v_rcp_f32_e32 v151, v151
	v_mul_f32_e32 v121, v121, v152
	v_mul_f32_e32 v0, v141, v0
	v_mul_f32_e32 v127, v127, v135
	v_mul_f32_e32 v131, v131, v147
	v_mul_f32_e32 v129, v129, v148
	v_mul_f32_e32 v133, v133, v149
	v_mul_f32_e32 v119, v119, v150
	v_mul_f32_e32 v135, v143, v151
	v_mul_f32_e32 v121, v120, v121
	v_mul_f32_e32 v0, v140, v0
	v_mul_f32_e32 v126, v126, v127
	v_mul_f32_e32 v127, v130, v131
	v_mul_f32_e32 v128, v128, v129
	v_mul_f32_e32 v129, v132, v133
	v_mul_f32_e32 v130, v118, v119
	v_mul_f32_e32 v131, v142, v135
	v_cvt_pk_bf16_f32 v118, v0, v126
	v_cvt_pk_bf16_f32 v119, v127, v128
	v_cvt_pk_bf16_f32 v120, v129, v130
	v_cvt_pk_bf16_f32 v121, v131, v121
	ds_write_b128 v164, v[118:121]
	ds_read_b128 v[168:171], v161
	v_lshl_add_u64 v[172:173], v[138:139], 0, v[166:167]
	s_waitcnt lgkmcnt(0)
	global_store_dwordx4 v[172:173], v[168:171], off
	global_load_dword v0, v[144:145], off
	s_waitcnt vmcnt(0)
	v_fmamk_f32 v0, v0, 0x3a800000, v236
	v_rsq_f32_e32 v0, v0
	v_mov_b32_e32 v119, v110
	v_mov_b32_e32 v110, v115
	v_mov_b32_e32 v115, v112
	v_mov_b32_e32 v112, v117
	v_mov_b32_e32 v117, v102
	v_mov_b32_e32 v102, v107
	v_mov_b32_e32 v107, v104
	v_mov_b32_e32 v104, v109
	v_mov_b32_e32 v118, v114
	v_mov_b32_e32 v114, v116
	v_mov_b32_e32 v116, v106
	v_mov_b32_e32 v106, v108
	v_or_b32_e32 v108, 32, v134
	v_pk_mul_f32 v[104:105], v[104:105], v[0:1] op_sel_hi:[1,0]
	v_ashrrev_i32_e32 v109, 31, v108
	v_pk_mul_f32 v[118:119], v[118:119], v[0:1] op_sel_hi:[1,0]
	v_pk_mul_f32 v[110:111], v[110:111], v[0:1] op_sel_hi:[1,0]
	v_pk_mul_f32 v[114:115], v[114:115], v[0:1] op_sel_hi:[1,0]
	v_pk_mul_f32 v[112:113], v[112:113], v[0:1] op_sel_hi:[1,0]
	v_pk_mul_f32 v[116:117], v[116:117], v[0:1] op_sel_hi:[1,0]
	v_pk_mul_f32 v[102:103], v[102:103], v[0:1] op_sel_hi:[1,0]
	v_pk_mul_f32 v[106:107], v[106:107], v[0:1] op_sel_hi:[1,0]
	v_mul_f32_e32 v133, 0xbfb8aa3b, v105
	v_lshl_add_u64 v[126:127], v[108:109], 2, s[14:15]
	v_mul_f32_e32 v0, 0xbfb8aa3b, v119
	v_mul_f32_e32 v109, 0xbfb8aa3b, v111
	v_mul_f32_e32 v128, 0xbfb8aa3b, v115
	v_mul_f32_e32 v129, 0xbfb8aa3b, v113
	v_mul_f32_e32 v130, 0xbfb8aa3b, v117
	v_mul_f32_e32 v131, 0xbfb8aa3b, v103
	v_mul_f32_e32 v132, 0xbfb8aa3b, v107
	v_exp_f32_e32 v133, v133
	v_exp_f32_e32 v0, v0
	v_exp_f32_e32 v109, v109
	v_exp_f32_e32 v128, v128
	v_exp_f32_e32 v129, v129
	v_exp_f32_e32 v130, v130
	v_exp_f32_e32 v131, v131
	v_exp_f32_e32 v132, v132
	v_add_f32_e32 v133, 1.0, v133
	v_add_f32_e32 v0, 1.0, v0
	v_add_f32_e32 v109, 1.0, v109
	v_add_f32_e32 v128, 1.0, v128
	v_add_f32_e32 v129, 1.0, v129
	v_add_f32_e32 v130, 1.0, v130
	v_add_f32_e32 v131, 1.0, v131
	v_add_f32_e32 v132, 1.0, v132
	v_rcp_f32_e32 v133, v133
	v_rcp_f32_e32 v0, v0
	v_rcp_f32_e32 v109, v109
	v_rcp_f32_e32 v128, v128
	v_rcp_f32_e32 v129, v129
	v_rcp_f32_e32 v130, v130
	v_rcp_f32_e32 v131, v131
	v_rcp_f32_e32 v132, v132
	v_mad_i64_i32 v[120:121], s[0:1], v146, s68, v[122:123]
	v_mul_f32_e32 v105, v105, v133
	v_lshl_add_u64 v[120:121], v[120:121], 0, v[124:125]
	v_mul_f32_e32 v0, v119, v0
	v_mul_f32_e32 v109, v111, v109
	v_mul_f32_e32 v111, v115, v128
	v_mul_f32_e32 v113, v113, v129
	v_mul_f32_e32 v115, v117, v130
	v_mul_f32_e32 v103, v103, v131
	v_mul_f32_e32 v107, v107, v132
	v_mul_f32_e32 v105, v104, v105
	v_mul_f32_e32 v0, v118, v0
	v_mul_f32_e32 v109, v110, v109
	v_mul_f32_e32 v110, v114, v111
	v_mul_f32_e32 v111, v112, v113
	v_mul_f32_e32 v112, v116, v115
	v_mul_f32_e32 v113, v102, v103
	v_mul_f32_e32 v106, v106, v107
	v_cvt_pk_bf16_f32 v102, v0, v109
	v_cvt_pk_bf16_f32 v103, v110, v111
	v_cvt_pk_bf16_f32 v104, v112, v113
	v_cvt_pk_bf16_f32 v105, v106, v105
	ds_write_b128 v164, v[102:105]
	ds_read_b128 v[168:171], v161
	v_lshl_add_u64 v[172:173], v[120:121], 0, v[166:167]
	s_waitcnt lgkmcnt(0)
; __device__ __forceinline__ unsigned cvt_pk_bf16(float lo, float hi) { unsigned r; asm volatile("v_cvt_pk_bf16_f32 %0, %1, %2" : "=v"(r) : "v"(lo), "v"(hi)); return r; }
; __device__ __forceinline__ float sigmoidf_(float x) { return __builtin_amdgcn_rcpf(1.f + __builtin_amdgcn_exp2f(-x * LOG2E)); }
;     __device__ __forceinline__ void operator()(const f32x4 (&acc)[2][2][4][2], const pg8::Unit& u, int wr, int wc, int fr, int fq) const {
;         const int row0 = u.pm * 256 + wr * 64 + fr, col0 = u.pn * 128 + wc * 32 + 8 * fq;
; #pragma unroll
;         for (int ai = 0; ai < 2; ++ai)
; #pragma unroll
;             for (int m = 0; m < 4; ++m) { const int row = row0 + ai * 128 + m * 16; const float rs = __builtin_amdgcn_rsqf(ss[row] * (1.f / DM) + EPS);
;                 float h[8];
; #pragma unroll
;                 for (int n = 0; n < 2; ++n)
; #pragma unroll
;                     for (int j = 0; j < 4; ++j) { const float g = acc[ai][0][m][n][j] * rs, up = acc[ai][1][m][n][j] * rs; h[4 * n + j] = g * sigmoidf_(g) * up; }
;                 u32x4 w; w.x = cvt_pk_bf16(h[0], h[1]); w.y = cvt_pk_bf16(h[2], h[3]); w.z = cvt_pk_bf16(h[4], h[5]); w.w = cvt_pk_bf16(h[6], h[7]);
;                 *(u32x4*)(H + (size_t)row * DFF + col0) = w; }
	global_store_dwordx4 v[172:173], v[168:171], off
	global_load_dword v0, v[126:127], off
	s_waitcnt vmcnt(0)
	v_fmamk_f32 v0, v0, 0x3a800000, v236
	v_rsq_f32_e32 v0, v0
	v_mov_b32_e32 v103, v94
	v_mov_b32_e32 v94, v99
	v_mov_b32_e32 v99, v96
	v_mov_b32_e32 v96, v101
	v_mov_b32_e32 v101, v86
	v_mov_b32_e32 v86, v91
	v_mov_b32_e32 v91, v88
	v_mov_b32_e32 v88, v93
	v_mov_b32_e32 v102, v98
	v_mov_b32_e32 v98, v100
	v_mov_b32_e32 v100, v90
	v_mov_b32_e32 v90, v92
	v_or_b32_e32 v92, 48, v134
	v_pk_mul_f32 v[88:89], v[88:89], v[0:1] op_sel_hi:[1,0]
	v_ashrrev_i32_e32 v93, 31, v92
	v_pk_mul_f32 v[102:103], v[102:103], v[0:1] op_sel_hi:[1,0]
	v_pk_mul_f32 v[94:95], v[94:95], v[0:1] op_sel_hi:[1,0]
	v_pk_mul_f32 v[98:99], v[98:99], v[0:1] op_sel_hi:[1,0]
	v_pk_mul_f32 v[96:97], v[96:97], v[0:1] op_sel_hi:[1,0]
	v_pk_mul_f32 v[100:101], v[100:101], v[0:1] op_sel_hi:[1,0]
	v_pk_mul_f32 v[86:87], v[86:87], v[0:1] op_sel_hi:[1,0]
	v_pk_mul_f32 v[90:91], v[90:91], v[0:1] op_sel_hi:[1,0]
	v_mul_f32_e32 v113, 0xbfb8aa3b, v89
	v_mad_i64_i32 v[104:105], s[0:1], v108, s68, v[122:123]
	v_lshl_add_u64 v[106:107], v[92:93], 2, s[14:15]
	v_mul_f32_e32 v0, 0xbfb8aa3b, v103
	v_mul_f32_e32 v93, 0xbfb8aa3b, v95
	v_mul_f32_e32 v108, 0xbfb8aa3b, v99
	v_mul_f32_e32 v109, 0xbfb8aa3b, v97
	v_mul_f32_e32 v110, 0xbfb8aa3b, v101
	v_mul_f32_e32 v111, 0xbfb8aa3b, v87
	v_mul_f32_e32 v112, 0xbfb8aa3b, v91
	v_exp_f32_e32 v113, v113
	v_exp_f32_e32 v0, v0
	v_exp_f32_e32 v93, v93
	v_exp_f32_e32 v108, v108
	v_exp_f32_e32 v109, v109
	v_exp_f32_e32 v110, v110
	v_exp_f32_e32 v111, v111
	v_exp_f32_e32 v112, v112
	v_add_f32_e32 v113, 1.0, v113
	v_add_f32_e32 v0, 1.0, v0
	v_add_f32_e32 v93, 1.0, v93
	v_add_f32_e32 v108, 1.0, v108
	v_add_f32_e32 v109, 1.0, v109
	v_add_f32_e32 v110, 1.0, v110
	v_add_f32_e32 v111, 1.0, v111
	v_add_f32_e32 v112, 1.0, v112
	v_rcp_f32_e32 v113, v113
	v_rcp_f32_e32 v0, v0
	v_rcp_f32_e32 v93, v93
	v_rcp_f32_e32 v108, v108
	v_rcp_f32_e32 v109, v109
	v_rcp_f32_e32 v110, v110
	v_rcp_f32_e32 v111, v111
	v_rcp_f32_e32 v112, v112
	v_mul_f32_e32 v89, v89, v113
	v_lshl_add_u64 v[104:105], v[104:105], 0, v[124:125]
	v_mul_f32_e32 v0, v103, v0
	v_mul_f32_e32 v93, v95, v93
	v_mul_f32_e32 v95, v99, v108
	v_mul_f32_e32 v97, v97, v109
	v_mul_f32_e32 v99, v101, v110
	v_mul_f32_e32 v87, v87, v111
	v_mul_f32_e32 v91, v91, v112
	v_mul_f32_e32 v89, v88, v89
	v_mul_f32_e32 v0, v102, v0
	v_mul_f32_e32 v93, v94, v93
	v_mul_f32_e32 v94, v98, v95
	v_mul_f32_e32 v95, v96, v97
	v_mul_f32_e32 v96, v100, v99
	v_mul_f32_e32 v97, v86, v87
	v_mul_f32_e32 v90, v90, v91
	v_cvt_pk_bf16_f32 v86, v0, v93
	v_cvt_pk_bf16_f32 v87, v94, v95
	v_cvt_pk_bf16_f32 v88, v96, v97
	v_cvt_pk_bf16_f32 v89, v90, v89
	ds_write_b128 v164, v[86:89]
	ds_read_b128 v[168:171], v161
	v_lshl_add_u64 v[172:173], v[104:105], 0, v[166:167]
	s_waitcnt lgkmcnt(0)
	global_store_dwordx4 v[172:173], v[168:171], off
	global_load_dword v0, v[106:107], off
	s_waitcnt vmcnt(0)
	v_fmamk_f32 v0, v0, 0x3a800000, v236
	v_rsq_f32_e32 v0, v0
	v_mov_b32_e32 v86, v82
	v_mov_b32_e32 v87, v78
	v_mov_b32_e32 v78, v83
	v_mov_b32_e32 v82, v84
	v_mov_b32_e32 v83, v80
	v_mov_b32_e32 v80, v85
	v_mov_b32_e32 v84, v70
	v_mov_b32_e32 v85, v74
	v_mov_b32_e32 v74, v71
	v_mov_b32_e32 v70, v72
	v_mov_b32_e32 v71, v76
	v_mov_b32_e32 v76, v73
	v_mad_i64_i32 v[72:73], s[0:1], v92, s68, v[122:123]
	v_lshl_add_u64 v[88:89], v[72:73], 0, v[124:125]
	v_pk_mul_f32 v[72:73], v[86:87], v[0:1] op_sel_hi:[1,0]
	v_pk_mul_f32 v[78:79], v[78:79], v[0:1] op_sel_hi:[1,0]
	v_pk_mul_f32 v[82:83], v[82:83], v[0:1] op_sel_hi:[1,0]
	v_pk_mul_f32 v[80:81], v[80:81], v[0:1] op_sel_hi:[1,0]
	v_pk_mul_f32 v[84:85], v[84:85], v[0:1] op_sel_hi:[1,0]
	v_pk_mul_f32 v[74:75], v[74:75], v[0:1] op_sel_hi:[1,0]
	v_pk_mul_f32 v[70:71], v[70:71], v[0:1] op_sel_hi:[1,0]
	v_pk_mul_f32 v[76:77], v[76:77], v[0:1] op_sel_hi:[1,0]
	v_mul_f32_e32 v0, 0xbfb8aa3b, v73
	v_mul_f32_e32 v86, 0xbfb8aa3b, v79
	v_mul_f32_e32 v87, 0xbfb8aa3b, v83
	v_mul_f32_e32 v90, 0xbfb8aa3b, v81
	v_mul_f32_e32 v91, 0xbfb8aa3b, v85
	v_mul_f32_e32 v92, 0xbfb8aa3b, v75
	v_mul_f32_e32 v93, 0xbfb8aa3b, v71
	v_mul_f32_e32 v94, 0xbfb8aa3b, v77
	v_exp_f32_e32 v0, v0
	v_exp_f32_e32 v86, v86
	v_exp_f32_e32 v87, v87
	v_exp_f32_e32 v90, v90
	v_exp_f32_e32 v91, v91
	v_exp_f32_e32 v92, v92
	v_exp_f32_e32 v93, v93
	v_exp_f32_e32 v94, v94
	v_add_f32_e32 v0, 1.0, v0
	v_add_f32_e32 v86, 1.0, v86
	v_add_f32_e32 v87, 1.0, v87
	v_add_f32_e32 v90, 1.0, v90
	v_add_f32_e32 v91, 1.0, v91
	v_add_f32_e32 v92, 1.0, v92
	v_add_f32_e32 v93, 1.0, v93
	v_add_f32_e32 v94, 1.0, v94
	v_rcp_f32_e32 v0, v0
	v_rcp_f32_e32 v86, v86
	v_rcp_f32_e32 v87, v87
	v_rcp_f32_e32 v90, v90
	v_rcp_f32_e32 v91, v91
	v_rcp_f32_e32 v92, v92
	v_rcp_f32_e32 v93, v93
	v_rcp_f32_e32 v94, v94
	v_mul_f32_e32 v0, v73, v0
	v_mul_f32_e32 v73, v79, v86
	v_mul_f32_e32 v79, v83, v87
	v_mul_f32_e32 v81, v81, v90
	v_mul_f32_e32 v83, v85, v91
	v_mul_f32_e32 v75, v75, v92
	v_mul_f32_e32 v71, v71, v93
	v_mul_f32_e32 v77, v77, v94
	v_mul_f32_e32 v0, v72, v0
	v_mul_f32_e32 v72, v78, v73
	v_mul_f32_e32 v73, v82, v79
	v_mul_f32_e32 v78, v80, v81
	v_mul_f32_e32 v79, v84, v83
	v_mul_f32_e32 v74, v74, v75
	v_mul_f32_e32 v75, v70, v71
	v_mul_f32_e32 v76, v76, v77
	v_cvt_pk_bf16_f32 v70, v0, v72
	v_cvt_pk_bf16_f32 v71, v73, v78
	v_cvt_pk_bf16_f32 v72, v79, v74
	v_cvt_pk_bf16_f32 v73, v75, v76
	ds_write_b128 v164, v[70:73]
	ds_read_b128 v[168:171], v161
	v_lshl_add_u64 v[172:173], v[88:89], 0, v[166:167]
	s_waitcnt lgkmcnt(0)
	global_store_dwordx4 v[172:173], v[168:171], off
	global_load_dword v0, v[136:137], off offset:512
	s_waitcnt vmcnt(0)
; __device__ __forceinline__ unsigned cvt_pk_bf16(float lo, float hi) { unsigned r; asm volatile("v_cvt_pk_bf16_f32 %0, %1, %2" : "=v"(r) : "v"(lo), "v"(hi)); return r; }
; __device__ __forceinline__ float sigmoidf_(float x) { return __builtin_amdgcn_rcpf(1.f + __builtin_amdgcn_exp2f(-x * LOG2E)); }
;     __device__ __forceinline__ void operator()(const f32x4 (&acc)[2][2][4][2], const pg8::Unit& u, int wr, int wc, int fr, int fq) const {
;     ...
;             for (int m = 0; m < 4; ++m) { const int row = row0 + ai * 128 + m * 16; const float rs = __builtin_amdgcn_rsqf(ss[row] * (1.f / DM) + EPS);
;                 float h[8];
; #pragma unroll
;                 for (int n = 0; n < 2; ++n)
; #pragma unroll
;                     for (int j = 0; j < 4; ++j) { const float g = acc[ai][0][m][n][j] * rs, up = acc[ai][1][m][n][j] * rs; h[4 * n + j] = g * sigmoidf_(g) * up; }
;                 u32x4 w; w.x = cvt_pk_bf16(h[0], h[1]); w.y = cvt_pk_bf16(h[2], h[3]); w.z = cvt_pk_bf16(h[4], h[5]); w.w = cvt_pk_bf16(h[6], h[7]);
;                 *(u32x4*)(H + (size_t)row * DFF + col0) = w; }
	v_fmamk_f32 v0, v0, 0x3a800000, v236
	v_rsq_f32_e32 v0, v0
	v_mov_b32_e32 v70, v66
	v_mov_b32_e32 v66, v68
	v_mov_b32_e32 v68, v54
	v_mov_b32_e32 v54, v56
	v_add_u32_e32 v56, 0x80, v134
	v_mov_b32_e32 v71, v62
	v_mov_b32_e32 v62, v67
	v_mov_b32_e32 v67, v64
	v_mov_b32_e32 v64, v69
	v_mov_b32_e32 v69, v58
	v_mov_b32_e32 v58, v55
	v_mov_b32_e32 v55, v60
	v_mov_b32_e32 v60, v57
	v_mad_i64_i32 v[56:57], s[0:1], v56, s68, v[122:123]
	v_lshl_add_u64 v[72:73], v[56:57], 0, v[124:125]
	v_pk_mul_f32 v[56:57], v[70:71], v[0:1] op_sel_hi:[1,0]
	v_pk_mul_f32 v[62:63], v[62:63], v[0:1] op_sel_hi:[1,0]
	v_pk_mul_f32 v[66:67], v[66:67], v[0:1] op_sel_hi:[1,0]
	v_pk_mul_f32 v[64:65], v[64:65], v[0:1] op_sel_hi:[1,0]
	v_pk_mul_f32 v[68:69], v[68:69], v[0:1] op_sel_hi:[1,0]
	v_pk_mul_f32 v[58:59], v[58:59], v[0:1] op_sel_hi:[1,0]
	v_pk_mul_f32 v[54:55], v[54:55], v[0:1] op_sel_hi:[1,0]
	v_pk_mul_f32 v[60:61], v[60:61], v[0:1] op_sel_hi:[1,0]
	v_mul_f32_e32 v0, 0xbfb8aa3b, v57
	v_mul_f32_e32 v70, 0xbfb8aa3b, v63
	v_mul_f32_e32 v71, 0xbfb8aa3b, v67
	v_mul_f32_e32 v74, 0xbfb8aa3b, v65
	v_mul_f32_e32 v75, 0xbfb8aa3b, v69
	v_mul_f32_e32 v76, 0xbfb8aa3b, v59
	v_mul_f32_e32 v77, 0xbfb8aa3b, v55
	v_mul_f32_e32 v78, 0xbfb8aa3b, v61
	v_exp_f32_e32 v0, v0
	v_exp_f32_e32 v70, v70
	v_exp_f32_e32 v71, v71
	v_exp_f32_e32 v74, v74
	v_exp_f32_e32 v75, v75
	v_exp_f32_e32 v76, v76
	v_exp_f32_e32 v77, v77
	v_exp_f32_e32 v78, v78
	v_add_f32_e32 v0, 1.0, v0
	v_add_f32_e32 v70, 1.0, v70
	v_add_f32_e32 v71, 1.0, v71
	v_add_f32_e32 v74, 1.0, v74
	v_add_f32_e32 v75, 1.0, v75
	v_add_f32_e32 v76, 1.0, v76
	v_add_f32_e32 v77, 1.0, v77
	v_add_f32_e32 v78, 1.0, v78
	v_rcp_f32_e32 v0, v0
	v_rcp_f32_e32 v70, v70
	v_rcp_f32_e32 v71, v71
	v_rcp_f32_e32 v74, v74
	v_rcp_f32_e32 v75, v75
	v_rcp_f32_e32 v76, v76
	v_rcp_f32_e32 v77, v77
	v_rcp_f32_e32 v78, v78
	v_mul_f32_e32 v0, v57, v0
	v_mul_f32_e32 v57, v63, v70
	v_mul_f32_e32 v63, v67, v71
	v_mul_f32_e32 v65, v65, v74
	v_mul_f32_e32 v67, v69, v75
	v_mul_f32_e32 v59, v59, v76
	v_mul_f32_e32 v55, v55, v77
	v_mul_f32_e32 v61, v61, v78
	v_mul_f32_e32 v0, v56, v0
	v_mul_f32_e32 v56, v62, v57
	v_mul_f32_e32 v57, v66, v63
	v_mul_f32_e32 v62, v64, v65
	v_mul_f32_e32 v63, v68, v67
	v_mul_f32_e32 v58, v58, v59
	v_mul_f32_e32 v59, v54, v55
	v_mul_f32_e32 v60, v60, v61
	v_cvt_pk_bf16_f32 v54, v0, v56
	v_cvt_pk_bf16_f32 v55, v57, v62
	v_cvt_pk_bf16_f32 v56, v63, v58
	v_cvt_pk_bf16_f32 v57, v59, v60
	ds_write_b128 v164, v[54:57]
	ds_read_b128 v[168:171], v161
	v_lshl_add_u64 v[172:173], v[72:73], 0, v[166:167]
	s_waitcnt lgkmcnt(0)
	global_store_dwordx4 v[172:173], v[168:171], off
	global_load_dword v0, v[136:137], off offset:576
	s_waitcnt vmcnt(0)
	v_fmamk_f32 v0, v0, 0x3a800000, v236
	v_rsq_f32_e32 v0, v0
	v_mov_b32_e32 v54, v50
	v_mov_b32_e32 v50, v52
	v_mov_b32_e32 v52, v38
	v_mov_b32_e32 v38, v40
	v_add_u32_e32 v40, 0x90, v134
	v_mov_b32_e32 v55, v46
	v_mov_b32_e32 v46, v51
	v_mov_b32_e32 v51, v48
	v_mov_b32_e32 v48, v53
	v_mov_b32_e32 v53, v42
	v_mov_b32_e32 v42, v39
	v_mov_b32_e32 v39, v44
	v_mov_b32_e32 v44, v41
	v_mad_i64_i32 v[40:41], s[0:1], v40, s68, v[122:123]
	v_lshl_add_u64 v[56:57], v[40:41], 0, v[124:125]
	v_pk_mul_f32 v[40:41], v[54:55], v[0:1] op_sel_hi:[1,0]
	v_pk_mul_f32 v[46:47], v[46:47], v[0:1] op_sel_hi:[1,0]
	v_pk_mul_f32 v[50:51], v[50:51], v[0:1] op_sel_hi:[1,0]
	v_pk_mul_f32 v[48:49], v[48:49], v[0:1] op_sel_hi:[1,0]
	v_pk_mul_f32 v[52:53], v[52:53], v[0:1] op_sel_hi:[1,0]
	v_pk_mul_f32 v[42:43], v[42:43], v[0:1] op_sel_hi:[1,0]
	v_pk_mul_f32 v[38:39], v[38:39], v[0:1] op_sel_hi:[1,0]
	v_pk_mul_f32 v[44:45], v[44:45], v[0:1] op_sel_hi:[1,0]
	v_mul_f32_e32 v0, 0xbfb8aa3b, v41
	v_mul_f32_e32 v54, 0xbfb8aa3b, v47
	v_mul_f32_e32 v55, 0xbfb8aa3b, v51
	v_mul_f32_e32 v58, 0xbfb8aa3b, v49
	v_mul_f32_e32 v59, 0xbfb8aa3b, v53
	v_mul_f32_e32 v60, 0xbfb8aa3b, v43
	v_mul_f32_e32 v61, 0xbfb8aa3b, v39
	v_mul_f32_e32 v62, 0xbfb8aa3b, v45
	v_exp_f32_e32 v0, v0
	v_exp_f32_e32 v54, v54
	v_exp_f32_e32 v55, v55
	v_exp_f32_e32 v58, v58
	v_exp_f32_e32 v59, v59
	v_exp_f32_e32 v60, v60
	v_exp_f32_e32 v61, v61
	v_exp_f32_e32 v62, v62
	v_add_f32_e32 v0, 1.0, v0
	v_add_f32_e32 v54, 1.0, v54
	v_add_f32_e32 v55, 1.0, v55
	v_add_f32_e32 v58, 1.0, v58
	v_add_f32_e32 v59, 1.0, v59
	v_add_f32_e32 v60, 1.0, v60
	v_add_f32_e32 v61, 1.0, v61
	v_add_f32_e32 v62, 1.0, v62
	v_rcp_f32_e32 v0, v0
	v_rcp_f32_e32 v54, v54
	v_rcp_f32_e32 v55, v55
	v_rcp_f32_e32 v58, v58
	v_rcp_f32_e32 v59, v59
	v_rcp_f32_e32 v60, v60
	v_rcp_f32_e32 v61, v61
	v_rcp_f32_e32 v62, v62
	v_mul_f32_e32 v0, v41, v0
	v_mul_f32_e32 v41, v47, v54
	v_mul_f32_e32 v47, v51, v55
	v_mul_f32_e32 v49, v49, v58
	v_mul_f32_e32 v51, v53, v59
	v_mul_f32_e32 v43, v43, v60
	v_mul_f32_e32 v39, v39, v61
	v_mul_f32_e32 v45, v45, v62
	v_mul_f32_e32 v0, v40, v0
	v_mul_f32_e32 v40, v46, v41
	v_mul_f32_e32 v41, v50, v47
	v_mul_f32_e32 v46, v48, v49
	v_mul_f32_e32 v47, v52, v51
	v_mul_f32_e32 v42, v42, v43
	v_mul_f32_e32 v43, v38, v39
	v_mul_f32_e32 v44, v44, v45
	v_cvt_pk_bf16_f32 v38, v0, v40
	v_cvt_pk_bf16_f32 v39, v41, v46
	v_cvt_pk_bf16_f32 v40, v47, v42
	v_cvt_pk_bf16_f32 v41, v43, v44
	ds_write_b128 v164, v[38:41]
	ds_read_b128 v[168:171], v161
	v_lshl_add_u64 v[172:173], v[56:57], 0, v[166:167]
	s_waitcnt lgkmcnt(0)
	global_store_dwordx4 v[172:173], v[168:171], off
	global_load_dword v0, v[136:137], off offset:640
	s_waitcnt vmcnt(0)
; __device__ __forceinline__ unsigned cvt_pk_bf16(float lo, float hi) { unsigned r; asm volatile("v_cvt_pk_bf16_f32 %0, %1, %2" : "=v"(r) : "v"(lo), "v"(hi)); return r; }
; __device__ __forceinline__ float sigmoidf_(float x) { return __builtin_amdgcn_rcpf(1.f + __builtin_amdgcn_exp2f(-x * LOG2E)); }
;     __device__ __forceinline__ void operator()(const f32x4 (&acc)[2][2][4][2], const pg8::Unit& u, int wr, int wc, int fr, int fq) const {
;     ...
;             for (int m = 0; m < 4; ++m) { const int row = row0 + ai * 128 + m * 16; const float rs = __builtin_amdgcn_rsqf(ss[row] * (1.f / DM) + EPS);
;                 float h[8];
; #pragma unroll
;                 for (int n = 0; n < 2; ++n)
; #pragma unroll
;                     for (int j = 0; j < 4; ++j) { const float g = acc[ai][0][m][n][j] * rs, up = acc[ai][1][m][n][j] * rs; h[4 * n + j] = g * sigmoidf_(g) * up; }
;                 u32x4 w; w.x = cvt_pk_bf16(h[0], h[1]); w.y = cvt_pk_bf16(h[2], h[3]); w.z = cvt_pk_bf16(h[4], h[5]); w.w = cvt_pk_bf16(h[6], h[7]);
;                 *(u32x4*)(H + (size_t)row * DFF + col0) = w; }
	v_fmamk_f32 v0, v0, 0x3a800000, v236
	v_rsq_f32_e32 v0, v0
	v_mov_b32_e32 v38, v34
	v_mov_b32_e32 v34, v36
	v_mov_b32_e32 v36, v22
	v_mov_b32_e32 v22, v24
	v_add_u32_e32 v24, 0xa0, v134
	v_mov_b32_e32 v39, v30
	v_mov_b32_e32 v30, v35
	v_mov_b32_e32 v35, v32
	v_mov_b32_e32 v32, v37
	v_mov_b32_e32 v37, v26
	v_mov_b32_e32 v26, v23
	v_mov_b32_e32 v23, v28
	v_mov_b32_e32 v28, v25
	v_mad_i64_i32 v[24:25], s[0:1], v24, s68, v[122:123]
	v_lshl_add_u64 v[40:41], v[24:25], 0, v[124:125]
	v_pk_mul_f32 v[24:25], v[38:39], v[0:1] op_sel_hi:[1,0]
	v_pk_mul_f32 v[30:31], v[30:31], v[0:1] op_sel_hi:[1,0]
	v_pk_mul_f32 v[34:35], v[34:35], v[0:1] op_sel_hi:[1,0]
	v_pk_mul_f32 v[32:33], v[32:33], v[0:1] op_sel_hi:[1,0]
	v_pk_mul_f32 v[36:37], v[36:37], v[0:1] op_sel_hi:[1,0]
	v_pk_mul_f32 v[26:27], v[26:27], v[0:1] op_sel_hi:[1,0]
	v_pk_mul_f32 v[22:23], v[22:23], v[0:1] op_sel_hi:[1,0]
	v_pk_mul_f32 v[28:29], v[28:29], v[0:1] op_sel_hi:[1,0]
	v_mul_f32_e32 v0, 0xbfb8aa3b, v25
	v_mul_f32_e32 v38, 0xbfb8aa3b, v31
	v_mul_f32_e32 v39, 0xbfb8aa3b, v35
	v_mul_f32_e32 v42, 0xbfb8aa3b, v33
	v_mul_f32_e32 v43, 0xbfb8aa3b, v37
	v_mul_f32_e32 v44, 0xbfb8aa3b, v27
	v_mul_f32_e32 v45, 0xbfb8aa3b, v23
	v_mul_f32_e32 v46, 0xbfb8aa3b, v29
	v_exp_f32_e32 v0, v0
	v_exp_f32_e32 v38, v38
	v_exp_f32_e32 v39, v39
	v_exp_f32_e32 v42, v42
	v_exp_f32_e32 v43, v43
	v_exp_f32_e32 v44, v44
	v_exp_f32_e32 v45, v45
	v_exp_f32_e32 v46, v46
	v_add_f32_e32 v0, 1.0, v0
	v_add_f32_e32 v38, 1.0, v38
	v_add_f32_e32 v39, 1.0, v39
	v_add_f32_e32 v42, 1.0, v42
	v_add_f32_e32 v43, 1.0, v43
	v_add_f32_e32 v44, 1.0, v44
	v_add_f32_e32 v45, 1.0, v45
	v_add_f32_e32 v46, 1.0, v46
	v_rcp_f32_e32 v0, v0
	v_rcp_f32_e32 v38, v38
	v_rcp_f32_e32 v39, v39
	v_rcp_f32_e32 v42, v42
	v_rcp_f32_e32 v43, v43
	v_rcp_f32_e32 v44, v44
	v_rcp_f32_e32 v45, v45
	v_rcp_f32_e32 v46, v46
	v_mul_f32_e32 v0, v25, v0
	v_mul_f32_e32 v25, v31, v38
	v_mul_f32_e32 v31, v35, v39
	v_mul_f32_e32 v33, v33, v42
	v_mul_f32_e32 v35, v37, v43
	v_mul_f32_e32 v27, v27, v44
	v_mul_f32_e32 v23, v23, v45
	v_mul_f32_e32 v29, v29, v46
	v_mul_f32_e32 v0, v24, v0
	v_mul_f32_e32 v24, v30, v25
	v_mul_f32_e32 v25, v34, v31
	v_mul_f32_e32 v30, v32, v33
	v_mul_f32_e32 v31, v36, v35
	v_mul_f32_e32 v26, v26, v27
	v_mul_f32_e32 v27, v22, v23
	v_mul_f32_e32 v28, v28, v29
	v_cvt_pk_bf16_f32 v22, v0, v24
	v_cvt_pk_bf16_f32 v23, v25, v30
	v_cvt_pk_bf16_f32 v24, v31, v26
	v_cvt_pk_bf16_f32 v25, v27, v28
	ds_write_b128 v164, v[22:25]
	ds_read_b128 v[168:171], v161
	v_lshl_add_u64 v[172:173], v[40:41], 0, v[166:167]
	s_waitcnt lgkmcnt(0)
	global_store_dwordx4 v[172:173], v[168:171], off
	global_load_dword v0, v[136:137], off offset:704
	s_waitcnt vmcnt(0)
	v_fmamk_f32 v0, v0, 0x3a800000, v236
	v_rsq_f32_e32 v0, v0
	v_mov_b32_e32 v22, v18
	v_mov_b32_e32 v18, v20
	v_mov_b32_e32 v20, v6
	v_mov_b32_e32 v6, v8
	v_add_u32_e32 v8, 0xb0, v134
	v_mov_b32_e32 v23, v14
	v_mov_b32_e32 v14, v19
	v_mov_b32_e32 v19, v16
	v_mov_b32_e32 v16, v21
	v_mov_b32_e32 v21, v10
	v_mov_b32_e32 v10, v7
	v_mov_b32_e32 v7, v12
	v_mov_b32_e32 v12, v9
	v_mad_i64_i32 v[8:9], s[0:1], v8, s68, v[122:123]
	v_lshl_add_u64 v[24:25], v[8:9], 0, v[124:125]
	v_pk_mul_f32 v[8:9], v[22:23], v[0:1] op_sel_hi:[1,0]
	v_pk_mul_f32 v[14:15], v[14:15], v[0:1] op_sel_hi:[1,0]
	v_pk_mul_f32 v[18:19], v[18:19], v[0:1] op_sel_hi:[1,0]
	v_pk_mul_f32 v[16:17], v[16:17], v[0:1] op_sel_hi:[1,0]
	v_pk_mul_f32 v[20:21], v[20:21], v[0:1] op_sel_hi:[1,0]
	v_pk_mul_f32 v[10:11], v[10:11], v[0:1] op_sel_hi:[1,0]
	v_pk_mul_f32 v[6:7], v[6:7], v[0:1] op_sel_hi:[1,0]
	v_pk_mul_f32 v[12:13], v[12:13], v[0:1] op_sel_hi:[1,0]
	v_mul_f32_e32 v0, 0xbfb8aa3b, v9
	v_mul_f32_e32 v22, 0xbfb8aa3b, v15
	v_mul_f32_e32 v23, 0xbfb8aa3b, v19
	v_mul_f32_e32 v26, 0xbfb8aa3b, v17
	v_mul_f32_e32 v27, 0xbfb8aa3b, v21
	v_mul_f32_e32 v28, 0xbfb8aa3b, v11
	v_mul_f32_e32 v29, 0xbfb8aa3b, v7
	v_mul_f32_e32 v30, 0xbfb8aa3b, v13
	v_exp_f32_e32 v0, v0
	v_exp_f32_e32 v22, v22
	v_exp_f32_e32 v23, v23
	v_exp_f32_e32 v26, v26
	v_exp_f32_e32 v27, v27
	v_exp_f32_e32 v28, v28
	v_exp_f32_e32 v29, v29
	v_exp_f32_e32 v30, v30
	v_add_f32_e32 v0, 1.0, v0
	v_add_f32_e32 v22, 1.0, v22
	v_add_f32_e32 v23, 1.0, v23
	v_add_f32_e32 v26, 1.0, v26
	v_add_f32_e32 v27, 1.0, v27
	v_add_f32_e32 v28, 1.0, v28
	v_add_f32_e32 v29, 1.0, v29
	v_add_f32_e32 v30, 1.0, v30
	v_rcp_f32_e32 v0, v0
	v_rcp_f32_e32 v22, v22
	v_rcp_f32_e32 v23, v23
	v_rcp_f32_e32 v26, v26
	v_rcp_f32_e32 v27, v27
	v_rcp_f32_e32 v28, v28
	v_rcp_f32_e32 v29, v29
	v_rcp_f32_e32 v30, v30
	v_mul_f32_e32 v0, v9, v0
	v_mul_f32_e32 v9, v15, v22
	v_mul_f32_e32 v15, v19, v23
	v_mul_f32_e32 v17, v17, v26
	v_mul_f32_e32 v19, v21, v27
	v_mul_f32_e32 v11, v11, v28
	v_mul_f32_e32 v7, v7, v29
	v_mul_f32_e32 v13, v13, v30
	v_mul_f32_e32 v0, v8, v0
	v_mul_f32_e32 v8, v14, v9
	v_mul_f32_e32 v9, v18, v15
	s_mov_b64 s[0:1], -1
	v_mul_f32_e32 v14, v16, v17
	v_mul_f32_e32 v15, v20, v19
	v_mul_f32_e32 v10, v10, v11
	v_mul_f32_e32 v11, v6, v7
	v_mul_f32_e32 v12, v12, v13
	v_cvt_pk_bf16_f32 v6, v0, v8
	v_cvt_pk_bf16_f32 v7, v9, v14
	v_cvt_pk_bf16_f32 v8, v15, v10
	v_cvt_pk_bf16_f32 v9, v11, v12
	ds_write_b128 v164, v[6:9]
	ds_read_b128 v[168:171], v161
	v_lshl_add_u64 v[172:173], v[24:25], 0, v[166:167]
	s_waitcnt lgkmcnt(0)
	global_store_dwordx4 v[172:173], v[168:171], off
	s_cbranch_vccnz .LBB0_1201
	s_andn2_b64 vcc, exec, s[6:7]
	s_cbranch_vccnz .LBB0_1200
	s_barrier
